# plus: drop 83 redundant canonicalising v_max in the relu-squared epilogue (store-data wait states kept with s_nop)
# speedup vs baseline: 1.0164x; 1.0068x over previous
; __device__ __forceinline__ unsigned pkbf(float lo, float hi) { f32x2p v = {lo, hi}; bf16x2p b = __builtin_convertvector(v, bf16x2p); return __builtin_bit_cast(unsigned, b); }
;     __device__ __forceinline__ void operator()(const f32x4 (&acc)[2][2][4][2], const Unit& u, int wr, int wc, int fr, int fq) const {
;     ...
;                         if constexpr (MODE == EPI_RELU2) {
; #pragma unroll
;                             for (int e = 0; e < 4; ++e) { float a = fmaxf(v0[e], 0.f), b = fmaxf(v1[e], 0.f); v0[e] = a * a; v1[e] = b * b; }
;                         }
;                         if constexpr (MODE == EPI_GATEMUL) {
;                             const u32x4 gw = *(const u32x4*)(G + off); v0 = v0 * bscale; v1 = v1 * bscale;
;                             v0[0] *= bflo(gw.x); v0[1] *= bfhi(gw.x); v0[2] *= bflo(gw.y); v0[3] *= bfhi(gw.y);
;                             v1[0] *= bflo(gw.z); v1[1] *= bfhi(gw.z); v1[2] *= bflo(gw.w); v1[3] *= bfhi(gw.w);
;                             if (!first) {
;                                 const u32x4 ow = *(const u32x4*)(O + off);
;                                 v0[0] += bflo(ow.x); v0[1] += bfhi(ow.x); v0[2] += bflo(ow.y); v0[3] += bfhi(ow.y);
;                                 v1[0] += bflo(ow.z); v1[1] += bfhi(ow.z); v1[2] += bflo(ow.w); v1[3] += bfhi(ow.w);
;                             }
;                         }
;                         u32x4 w; w.x = pkbf(v0[0], v0[1]); w.y = pkbf(v0[2], v0[3]); w.z = pkbf(v1[0], v1[1]); w.w = pkbf(v1[2], v1[3]);
;                         *(u32x4*)(O + off) = w;
.LBB0_859:
	v_lshl_add_u32 v130, s57, 8, v160
	v_max_f32_e32 v126, 0, v126
	v_max_f32_e32 v122, 0, v122
	v_max_f32_e32 v127, 0, v127
	v_max_f32_e32 v123, 0, v123
	v_lshl_or_b32 v132, s56, 8, v162
	v_ashrrev_i32_e32 v131, 31, v130
	v_pk_mul_f32 v[126:127], v[126:127], v[126:127]
	v_pk_mul_f32 v[122:123], v[122:123], v[122:123]
	v_max_f32_e32 v128, 0, v128
	v_max_f32_e32 v124, 0, v124
	v_max_f32_e32 v129, 0, v129
	v_max_f32_e32 v125, 0, v125
	v_ashrrev_i32_e32 v133, 31, v132
	v_pk_mul_f32 v[128:129], v[128:129], v[128:129]
	v_pk_mul_f32 v[164:165], v[124:125], v[124:125]
	v_cvt_pk_bf16_f32 v124, v126, v127
	v_cvt_pk_bf16_f32 v126, v122, v123
	v_lshlrev_b64 v[122:123], 13, v[130:131]
	v_cvt_pk_bf16_f32 v125, v128, v129
	v_lshl_add_u64 v[122:123], s[24:25], 0, v[122:123]
	v_lshlrev_b64 v[128:129], 1, v[132:133]
	v_cvt_pk_bf16_f32 v127, v164, v165
	v_lshl_add_u64 v[122:123], v[122:123], 0, v[128:129]
	v_max_f32_e32 v114, 0, v114
	v_max_f32_e32 v115, 0, v115
	global_store_dwordx4 v[122:123], v[124:127], off
	s_nop 1
	v_pk_mul_f32 v[124:125], v[114:115], v[114:115]
	v_max_f32_e32 v115, v116, v116
	v_max_f32_e32 v114, v120, v120
	v_max_f32_e32 v116, 0, v115
	v_max_f32_e32 v115, v121, v121
	v_max_f32_e32 v118, 0, v118
	v_max_f32_e32 v119, 0, v119
	v_max_f32_e32 v114, 0, v114
	v_max_f32_e32 v115, 0, v115
	v_max_f32_e32 v117, 0, v117
	v_pk_mul_f32 v[118:119], v[118:119], v[118:119]
	v_pk_mul_f32 v[120:121], v[114:115], v[114:115]
	v_pk_mul_f32 v[126:127], v[116:117], v[116:117]
	v_cvt_pk_bf16_f32 v114, v118, v119
	v_cvt_pk_bf16_f32 v115, v120, v121
	v_cvt_pk_bf16_f32 v116, v124, v125
	v_cvt_pk_bf16_f32 v117, v126, v127
	v_max_f32_e32 v106, 0, v106
	v_max_f32_e32 v107, 0, v107
	global_store_dwordx4 v[122:123], v[114:117], off offset:256
	s_nop 1
	v_pk_mul_f32 v[116:117], v[106:107], v[106:107]
	v_max_f32_e32 v107, v108, v108
	v_or_b32_e32 v114, 16, v130
	v_max_f32_e32 v110, 0, v110
	v_max_f32_e32 v111, 0, v111
	v_max_f32_e32 v106, v112, v112
	v_max_f32_e32 v108, 0, v107
	v_max_f32_e32 v107, v113, v113
	v_ashrrev_i32_e32 v115, 31, v114
	v_pk_mul_f32 v[110:111], v[110:111], v[110:111]
	v_max_f32_e32 v106, 0, v106
	v_max_f32_e32 v107, 0, v107
	v_max_f32_e32 v109, 0, v109
	v_pk_mul_f32 v[112:113], v[106:107], v[106:107]
	v_cvt_pk_bf16_f32 v106, v110, v111
	v_lshlrev_b64 v[110:111], 13, v[114:115]
	v_pk_mul_f32 v[118:119], v[108:109], v[108:109]
	v_lshl_add_u64 v[110:111], s[24:25], 0, v[110:111]
	v_cvt_pk_bf16_f32 v107, v112, v113
	v_cvt_pk_bf16_f32 v108, v116, v117
	v_cvt_pk_bf16_f32 v109, v118, v119
	v_lshl_add_u64 v[110:111], v[110:111], 0, v[128:129]
	v_max_f32_e32 v98, 0, v98
	v_max_f32_e32 v99, 0, v99
	global_store_dwordx4 v[110:111], v[106:109], off
	s_nop 1
	v_pk_mul_f32 v[106:107], v[98:99], v[98:99]
	v_max_f32_e32 v99, v100, v100
	v_max_f32_e32 v98, v104, v104
	v_max_f32_e32 v100, 0, v99
	v_max_f32_e32 v99, v105, v105
	v_max_f32_e32 v102, 0, v102
	v_max_f32_e32 v103, 0, v103
	v_max_f32_e32 v98, 0, v98
	v_max_f32_e32 v99, 0, v99
	v_max_f32_e32 v101, 0, v101
	v_pk_mul_f32 v[102:103], v[102:103], v[102:103]
	v_pk_mul_f32 v[104:105], v[98:99], v[98:99]
	v_pk_mul_f32 v[108:109], v[100:101], v[100:101]
	v_cvt_pk_bf16_f32 v98, v102, v103
	v_cvt_pk_bf16_f32 v99, v104, v105
	v_cvt_pk_bf16_f32 v100, v106, v107
	v_cvt_pk_bf16_f32 v101, v108, v109
	v_max_f32_e32 v90, 0, v90
	v_max_f32_e32 v91, 0, v91
	global_store_dwordx4 v[110:111], v[98:101], off offset:256
	s_nop 1
	v_pk_mul_f32 v[100:101], v[90:91], v[90:91]
	v_max_f32_e32 v91, v92, v92
	v_or_b32_e32 v98, 32, v130
	v_max_f32_e32 v94, 0, v94
	v_max_f32_e32 v95, 0, v95
	v_max_f32_e32 v90, v96, v96
	v_max_f32_e32 v92, 0, v91
	v_max_f32_e32 v91, v97, v97
	v_ashrrev_i32_e32 v99, 31, v98
	v_pk_mul_f32 v[94:95], v[94:95], v[94:95]
	v_max_f32_e32 v90, 0, v90
	v_max_f32_e32 v91, 0, v91
	v_max_f32_e32 v93, 0, v93
	v_pk_mul_f32 v[96:97], v[90:91], v[90:91]
	v_cvt_pk_bf16_f32 v90, v94, v95
	v_lshlrev_b64 v[94:95], 13, v[98:99]
	v_pk_mul_f32 v[102:103], v[92:93], v[92:93]
	v_lshl_add_u64 v[94:95], s[24:25], 0, v[94:95]
	v_cvt_pk_bf16_f32 v91, v96, v97
	v_cvt_pk_bf16_f32 v92, v100, v101
	v_cvt_pk_bf16_f32 v93, v102, v103
	v_lshl_add_u64 v[94:95], v[94:95], 0, v[128:129]
	v_max_f32_e32 v82, 0, v82
	v_max_f32_e32 v83, 0, v83
	global_store_dwordx4 v[94:95], v[90:93], off
	s_nop 1
	v_pk_mul_f32 v[90:91], v[82:83], v[82:83]
	v_max_f32_e32 v83, v84, v84
	v_max_f32_e32 v82, v88, v88
	v_max_f32_e32 v84, 0, v83
	v_max_f32_e32 v83, v89, v89
	v_max_f32_e32 v86, 0, v86
	v_max_f32_e32 v87, 0, v87
	v_max_f32_e32 v82, 0, v82
	v_max_f32_e32 v83, 0, v83
	v_max_f32_e32 v85, 0, v85
	v_pk_mul_f32 v[86:87], v[86:87], v[86:87]
	v_pk_mul_f32 v[88:89], v[82:83], v[82:83]
	v_pk_mul_f32 v[92:93], v[84:85], v[84:85]
	v_cvt_pk_bf16_f32 v82, v86, v87
	v_cvt_pk_bf16_f32 v83, v88, v89
	v_cvt_pk_bf16_f32 v84, v90, v91
	v_cvt_pk_bf16_f32 v85, v92, v93
	v_max_f32_e32 v74, 0, v74
	v_max_f32_e32 v75, 0, v75
	global_store_dwordx4 v[94:95], v[82:85], off offset:256
	s_nop 1
	v_pk_mul_f32 v[84:85], v[74:75], v[74:75]
	v_max_f32_e32 v75, v76, v76
	v_or_b32_e32 v82, 48, v130
	v_max_f32_e32 v78, 0, v78
	v_max_f32_e32 v79, 0, v79
	v_max_f32_e32 v74, v80, v80
	v_max_f32_e32 v76, 0, v75
	v_max_f32_e32 v75, v81, v81
	v_ashrrev_i32_e32 v83, 31, v82
	v_pk_mul_f32 v[78:79], v[78:79], v[78:79]
	v_max_f32_e32 v74, 0, v74
	v_max_f32_e32 v75, 0, v75
	v_max_f32_e32 v77, 0, v77
	v_pk_mul_f32 v[80:81], v[74:75], v[74:75]
	v_cvt_pk_bf16_f32 v74, v78, v79
	v_lshlrev_b64 v[78:79], 13, v[82:83]
	v_pk_mul_f32 v[86:87], v[76:77], v[76:77]
	v_lshl_add_u64 v[78:79], s[24:25], 0, v[78:79]
	v_cvt_pk_bf16_f32 v75, v80, v81
	v_cvt_pk_bf16_f32 v76, v84, v85
	v_cvt_pk_bf16_f32 v77, v86, v87
; __device__ __forceinline__ unsigned pkbf(float lo, float hi) { f32x2p v = {lo, hi}; bf16x2p b = __builtin_convertvector(v, bf16x2p); return __builtin_bit_cast(unsigned, b); }
;     __device__ __forceinline__ void operator()(const f32x4 (&acc)[2][2][4][2], const Unit& u, int wr, int wc, int fr, int fq) const {
;     ...
;                         if constexpr (MODE == EPI_RELU2) {
; #pragma unroll
;                             for (int e = 0; e < 4; ++e) { float a = fmaxf(v0[e], 0.f), b = fmaxf(v1[e], 0.f); v0[e] = a * a; v1[e] = b * b; }
;                         }
;                         if constexpr (MODE == EPI_GATEMUL) {
;                             const u32x4 gw = *(const u32x4*)(G + off); v0 = v0 * bscale; v1 = v1 * bscale;
;                             v0[0] *= bflo(gw.x); v0[1] *= bfhi(gw.x); v0[2] *= bflo(gw.y); v0[3] *= bfhi(gw.y);
;                             v1[0] *= bflo(gw.z); v1[1] *= bfhi(gw.z); v1[2] *= bflo(gw.w); v1[3] *= bfhi(gw.w);
;                             if (!first) {
;                                 const u32x4 ow = *(const u32x4*)(O + off);
;                                 v0[0] += bflo(ow.x); v0[1] += bfhi(ow.x); v0[2] += bflo(ow.y); v0[3] += bfhi(ow.y);
;                                 v1[0] += bflo(ow.z); v1[1] += bfhi(ow.z); v1[2] += bflo(ow.w); v1[3] += bfhi(ow.w);
;                             }
;                         }
;                         u32x4 w; w.x = pkbf(v0[0], v0[1]); w.y = pkbf(v0[2], v0[3]); w.z = pkbf(v1[0], v1[1]); w.w = pkbf(v1[2], v1[3]);
;                         *(u32x4*)(O + off) = w;
	v_lshl_add_u64 v[78:79], v[78:79], 0, v[128:129]
	v_max_f32_e32 v66, 0, v66
	v_max_f32_e32 v67, 0, v67
	global_store_dwordx4 v[78:79], v[74:77], off
	s_nop 1
	v_pk_mul_f32 v[74:75], v[66:67], v[66:67]
	v_max_f32_e32 v67, v68, v68
	v_max_f32_e32 v66, v72, v72
	v_max_f32_e32 v68, 0, v67
	v_max_f32_e32 v67, v73, v73
	v_max_f32_e32 v70, 0, v70
	v_max_f32_e32 v71, 0, v71
	v_max_f32_e32 v66, 0, v66
	v_max_f32_e32 v67, 0, v67
	v_max_f32_e32 v69, 0, v69
	v_pk_mul_f32 v[70:71], v[70:71], v[70:71]
	v_pk_mul_f32 v[72:73], v[66:67], v[66:67]
	v_pk_mul_f32 v[76:77], v[68:69], v[68:69]
	v_cvt_pk_bf16_f32 v66, v70, v71
	v_cvt_pk_bf16_f32 v67, v72, v73
	v_cvt_pk_bf16_f32 v68, v74, v75
	v_cvt_pk_bf16_f32 v69, v76, v77
	v_max_f32_e32 v58, 0, v58
	v_max_f32_e32 v59, 0, v59
	global_store_dwordx4 v[78:79], v[66:69], off offset:256
	s_nop 1
	v_pk_mul_f32 v[66:67], v[58:59], v[58:59]
	v_max_f32_e32 v59, v60, v60
	v_max_f32_e32 v58, v64, v64
	v_max_f32_e32 v60, 0, v59
	v_max_f32_e32 v59, v65, v65
	v_max_f32_e32 v58, 0, v58
	v_max_f32_e32 v59, 0, v59
	v_max_f32_e32 v62, 0, v62
	v_max_f32_e32 v63, 0, v63
	v_max_f32_e32 v61, 0, v61
	v_pk_mul_f32 v[64:65], v[58:59], v[58:59]
	s_mov_b32 s4, 0x100000
	v_pk_mul_f32 v[62:63], v[62:63], v[62:63]
	v_pk_mul_f32 v[68:69], v[60:61], v[60:61]
	v_cvt_pk_bf16_f32 v59, v64, v65
	v_add_co_u32_e32 v64, vcc, s4, v122
	v_cvt_pk_bf16_f32 v58, v62, v63
	v_cvt_pk_bf16_f32 v60, v66, v67
	v_cvt_pk_bf16_f32 v61, v68, v69
	v_addc_co_u32_e32 v65, vcc, 0, v123, vcc
	v_max_f32_e32 v50, 0, v50
	v_max_f32_e32 v51, 0, v51
	global_store_dwordx4 v[64:65], v[58:61], off
	s_nop 1
	v_pk_mul_f32 v[58:59], v[50:51], v[50:51]
	v_max_f32_e32 v51, v52, v52
	v_max_f32_e32 v50, v56, v56
	v_max_f32_e32 v52, 0, v51
	v_max_f32_e32 v51, v57, v57
	v_max_f32_e32 v54, 0, v54
	v_max_f32_e32 v55, 0, v55
	v_max_f32_e32 v50, 0, v50
	v_max_f32_e32 v51, 0, v51
	v_max_f32_e32 v53, 0, v53
	s_mov_b64 s[10:11], 0x100000
	v_pk_mul_f32 v[54:55], v[54:55], v[54:55]
	v_pk_mul_f32 v[56:57], v[50:51], v[50:51]
	v_pk_mul_f32 v[60:61], v[52:53], v[52:53]
	v_lshl_add_u64 v[62:63], v[122:123], 0, s[10:11]
	v_cvt_pk_bf16_f32 v50, v54, v55
	v_cvt_pk_bf16_f32 v51, v56, v57
	v_cvt_pk_bf16_f32 v52, v58, v59
	v_cvt_pk_bf16_f32 v53, v60, v61
	v_max_f32_e32 v42, 0, v42
	v_max_f32_e32 v43, 0, v43
	global_store_dwordx4 v[62:63], v[50:53], off offset:256
	s_nop 1
	v_pk_mul_f32 v[50:51], v[42:43], v[42:43]
	v_max_f32_e32 v43, v44, v44
	v_max_f32_e32 v42, v48, v48
	v_max_f32_e32 v44, 0, v43
	v_max_f32_e32 v43, v49, v49
	v_max_f32_e32 v42, 0, v42
	v_max_f32_e32 v43, 0, v43
	v_max_f32_e32 v46, 0, v46
	v_max_f32_e32 v47, 0, v47
	v_max_f32_e32 v45, 0, v45
	v_pk_mul_f32 v[48:49], v[42:43], v[42:43]
	s_mov_b32 s4, 0x120000
	v_pk_mul_f32 v[46:47], v[46:47], v[46:47]
	v_pk_mul_f32 v[52:53], v[44:45], v[44:45]
	v_cvt_pk_bf16_f32 v43, v48, v49
	v_add_co_u32_e32 v48, vcc, s4, v122
	v_cvt_pk_bf16_f32 v42, v46, v47
	v_cvt_pk_bf16_f32 v44, v50, v51
	v_cvt_pk_bf16_f32 v45, v52, v53
	v_addc_co_u32_e32 v49, vcc, 0, v123, vcc
	v_max_f32_e32 v34, 0, v34
	v_max_f32_e32 v35, 0, v35
	global_store_dwordx4 v[48:49], v[42:45], off
	s_nop 1
	v_pk_mul_f32 v[42:43], v[34:35], v[34:35]
	v_max_f32_e32 v35, v36, v36
	v_max_f32_e32 v34, v40, v40
	v_max_f32_e32 v36, 0, v35
	v_max_f32_e32 v35, v41, v41
	v_max_f32_e32 v38, 0, v38
	v_max_f32_e32 v39, 0, v39
	v_max_f32_e32 v34, 0, v34
	v_max_f32_e32 v35, 0, v35
	v_max_f32_e32 v37, 0, v37
	s_mov_b64 s[10:11], 0x120000
	v_pk_mul_f32 v[38:39], v[38:39], v[38:39]
	v_pk_mul_f32 v[40:41], v[34:35], v[34:35]
	v_pk_mul_f32 v[44:45], v[36:37], v[36:37]
	v_lshl_add_u64 v[46:47], v[122:123], 0, s[10:11]
	v_cvt_pk_bf16_f32 v34, v38, v39
	v_cvt_pk_bf16_f32 v35, v40, v41
	v_cvt_pk_bf16_f32 v36, v42, v43
	v_cvt_pk_bf16_f32 v37, v44, v45
	v_max_f32_e32 v26, 0, v26
	v_max_f32_e32 v27, 0, v27
	global_store_dwordx4 v[46:47], v[34:37], off offset:256
	s_nop 1
	v_pk_mul_f32 v[34:35], v[26:27], v[26:27]
	v_max_f32_e32 v27, v28, v28
	v_max_f32_e32 v26, v32, v32
	v_max_f32_e32 v28, 0, v27
	v_max_f32_e32 v27, v33, v33
	v_max_f32_e32 v26, 0, v26
	v_max_f32_e32 v27, 0, v27
	v_max_f32_e32 v30, 0, v30
	v_max_f32_e32 v31, 0, v31
	v_max_f32_e32 v29, 0, v29
	v_pk_mul_f32 v[32:33], v[26:27], v[26:27]
	s_mov_b32 s4, 0x140000
	v_pk_mul_f32 v[30:31], v[30:31], v[30:31]
	v_pk_mul_f32 v[36:37], v[28:29], v[28:29]
	v_cvt_pk_bf16_f32 v27, v32, v33
	v_add_co_u32_e32 v32, vcc, s4, v122
	v_cvt_pk_bf16_f32 v26, v30, v31
	v_cvt_pk_bf16_f32 v28, v34, v35
	v_cvt_pk_bf16_f32 v29, v36, v37
	v_addc_co_u32_e32 v33, vcc, 0, v123, vcc
	v_max_f32_e32 v18, 0, v18
	v_max_f32_e32 v19, 0, v19
	global_store_dwordx4 v[32:33], v[26:29], off
	s_nop 1
	v_pk_mul_f32 v[26:27], v[18:19], v[18:19]
	v_max_f32_e32 v19, v20, v20
	v_max_f32_e32 v18, v24, v24
	v_max_f32_e32 v20, 0, v19
	v_max_f32_e32 v19, v25, v25
	v_max_f32_e32 v22, 0, v22
	v_max_f32_e32 v23, 0, v23
	v_max_f32_e32 v18, 0, v18
	v_max_f32_e32 v19, 0, v19
	v_max_f32_e32 v21, 0, v21
	s_mov_b64 s[10:11], 0x140000
	v_pk_mul_f32 v[22:23], v[22:23], v[22:23]
	v_pk_mul_f32 v[24:25], v[18:19], v[18:19]
	v_pk_mul_f32 v[28:29], v[20:21], v[20:21]
	v_lshl_add_u64 v[30:31], v[122:123], 0, s[10:11]
	v_cvt_pk_bf16_f32 v18, v22, v23
	v_cvt_pk_bf16_f32 v19, v24, v25
	v_cvt_pk_bf16_f32 v20, v26, v27
	v_cvt_pk_bf16_f32 v21, v28, v29
	v_max_f32_e32 v10, 0, v10
	v_max_f32_e32 v11, 0, v11
	global_store_dwordx4 v[30:31], v[18:21], off offset:256
	s_nop 1
	v_pk_mul_f32 v[18:19], v[10:11], v[10:11]
	v_max_f32_e32 v11, v12, v12
	v_max_f32_e32 v10, v16, v16
	v_max_f32_e32 v12, 0, v11
	v_max_f32_e32 v11, v17, v17
	v_max_f32_e32 v10, 0, v10
	v_max_f32_e32 v11, 0, v11
	v_max_f32_e32 v14, 0, v14
	v_max_f32_e32 v15, 0, v15
	v_max_f32_e32 v13, 0, v13
	v_pk_mul_f32 v[16:17], v[10:11], v[10:11]
	s_mov_b32 s4, 0x160000
	v_pk_mul_f32 v[14:15], v[14:15], v[14:15]
	v_pk_mul_f32 v[20:21], v[12:13], v[12:13]
	v_cvt_pk_bf16_f32 v11, v16, v17
	v_add_co_u32_e32 v16, vcc, s4, v122
	v_cvt_pk_bf16_f32 v10, v14, v15
	v_cvt_pk_bf16_f32 v12, v18, v19
	v_cvt_pk_bf16_f32 v13, v20, v21
	v_addc_co_u32_e32 v17, vcc, 0, v123, vcc
	v_max_f32_e32 v2, 0, v2
	v_max_f32_e32 v3, 0, v3
	global_store_dwordx4 v[16:17], v[10:13], off
	s_nop 1
	v_pk_mul_f32 v[10:11], v[2:3], v[2:3]
	v_max_f32_e32 v3, v4, v4
	v_max_f32_e32 v2, v8, v8
	v_max_f32_e32 v4, 0, v3
	v_max_f32_e32 v3, v9, v9
	v_max_f32_e32 v6, 0, v6
	v_max_f32_e32 v7, 0, v7
	v_max_f32_e32 v2, 0, v2
	v_max_f32_e32 v3, 0, v3
	v_max_f32_e32 v5, 0, v5
	s_mov_b64 s[10:11], 0x160000
	v_pk_mul_f32 v[6:7], v[6:7], v[6:7]
	v_pk_mul_f32 v[8:9], v[2:3], v[2:3]
	v_pk_mul_f32 v[12:13], v[4:5], v[4:5]
	v_lshl_add_u64 v[14:15], v[122:123], 0, s[10:11]
	v_cvt_pk_bf16_f32 v2, v6, v7
	v_cvt_pk_bf16_f32 v3, v8, v9
	v_cvt_pk_bf16_f32 v4, v10, v11
	v_cvt_pk_bf16_f32 v5, v12, v13
	s_andn2_b64 vcc, exec, s[38:39]
	s_mov_b64 s[38:39], -1
	global_store_dwordx4 v[14:15], v[2:5], off offset:256
	s_cbranch_vccnz .LBB0_848
	s_andn2_b64 vcc, exec, s[0:1]
	s_cbranch_vccnz .LBB0_847
	s_barrier
	s_branch .LBB0_847
